# attention unit prologue: Q spill loads issued together with K/V tile 0 (was 8 serialised round trips)
# baseline (speedup 1.0000x reference)
.LBB0_728:
	v_mov_b32_e32 v0, s85
	ds_read_b32 v0, v0
	s_mov_b64 s[0:1], -1
	s_waitcnt lgkmcnt(0)
	v_readfirstlane_b32 s4, v0
	s_cmp_ge_i32 s4, s30
	s_cbranch_scc1 .LBB0_727
	s_and_b32 s0, s4, 7
	v_readlane_b32 s1, v255, 52
	s_or_b32 s5, s0, s1
	v_readlane_b32 s0, v255, 48
	s_and_b32 s10, s4, 63
	v_readlane_b32 s1, v255, 49
	s_and_b64 s[0:1], s[0:1], exec
	v_readlane_b32 s0, v255, 53
	s_cselect_b32 s58, s5, s10
	s_ashr_i32 s0, s4, s0
	v_readfirstlane_b32 s1, v134
	s_ashr_i32 s13, s1, 6
	s_lshl_b32 s4, s0, 8
	s_sub_i32 s5, 0x700, s4
	s_lshl_b32 s10, s13, 5
	s_sub_i32 s16, 0x800, s4
	s_lshl_b32 s28, s58, 11
	s_lshl_b32 s17, s58, 19
	s_ashr_i32 s0, s5, 31
	s_ashr_i32 s12, s10, 31
	s_add_u32 s59, s10, s5
	s_addc_u32 s76, s12, s0
	v_mov_b32_e32 v3, s76
	v_or_b32_e32 v2, s59, v136
	s_and_b32 s0, s1, 0x3fffffc0
	v_lshl_add_u64 v[2:3], v[2:3], 0, s[28:29]
	s_lshl_b32 s0, s0, 2
	s_movk_i32 s18, 0x180
	s_add_i32 s12, s0, 0
	v_mad_u64_u32 v[6:7], s[0:1], v2, s18, v[184:185]
	v_mad_i32_i24 v7, v3, s18, v7
	global_load_dwordx4 v[98:101], v[6:7], off
	global_load_dwordx4 v[102:105], v[6:7], off offset:32
	global_load_dwordx4 v[106:109], v[6:7], off offset:64
	global_load_dwordx4 v[110:113], v[6:7], off offset:96
	global_load_dwordx4 v[8:11], v[6:7], off offset:128
	global_load_dwordx4 v[12:15], v[6:7], off offset:160
	global_load_dwordx4 v[16:19], v[6:7], off offset:192
	global_load_dwordx4 v[20:23], v[6:7], off offset:224
	global_load_dwordx4 v[24:27], v[6:7], off offset:256
	global_load_dwordx4 v[28:31], v[6:7], off offset:288
	global_load_dwordx4 v[32:35], v[6:7], off offset:320
	global_load_dwordx4 v[36:39], v[6:7], off offset:352
	s_mul_i32 s11, s58, 0xc0000
	s_add_i32 s12, s12, 0x14000
	s_add_u32 s14, s90, s11
	s_addc_u32 s15, s91, 0
	s_lshl_b32 s0, s13, 13
	v_add_u32_e32 v220, s0, v137
	s_ashr_i32 s77, s16, 6
	s_add_u32 s0, s96, s17
	s_addc_u32 s1, s97, 0
	v_lshlrev_b32_e32 v0, 1, v140
	s_cmp_lt_i32 s77, 1
	v_lshl_add_u32 v218, v136, 2, s12
	v_lshl_add_u32 v217, v135, 2, s12
	v_lshl_add_u64 v[2:3], s[0:1], 0, v[148:149]
	v_lshl_add_u64 v[2:3], v[2:3], 0, v[0:1]
	global_load_dwordx4 v[114:117], v[2:3], off
	v_lshl_add_u64 v[2:3], s[0:1], 0, v[150:151]
	v_lshl_add_u64 v[2:3], v[2:3], 0, v[0:1]
	global_load_dwordx4 v[118:121], v[2:3], off
	v_lshl_add_u64 v[2:3], v[142:143], 1, s[14:15]
	global_load_dwordx4 v[122:125], v[2:3], off
	v_lshl_add_u64 v[2:3], v[144:145], 1, s[14:15]
	global_load_dwordx4 v[126:129], v[2:3], off
	v_lshl_add_u64 v[2:3], v[146:147], 1, s[14:15]
	global_load_dwordx4 v[130:133], v[2:3], off
	s_waitcnt vmcnt(12)
	ds_write_b128 v220, v[8:11]
	s_waitcnt vmcnt(11)
	ds_write_b128 v220, v[12:15] offset:1024
	s_waitcnt vmcnt(10)
	ds_write_b128 v220, v[16:19] offset:2048
	s_waitcnt vmcnt(9)
	ds_write_b128 v220, v[20:23] offset:3072
	s_waitcnt vmcnt(8)
	ds_write_b128 v220, v[24:27] offset:4096
	s_waitcnt vmcnt(7)
	ds_write_b128 v220, v[28:31] offset:5120
	s_waitcnt vmcnt(6)
	ds_write_b128 v220, v[32:35] offset:6144
	s_waitcnt vmcnt(5)
	ds_write_b128 v220, v[36:39] offset:7168
	s_waitcnt vmcnt(0)
	s_waitcnt vmcnt(2)
	ds_write_b128 v211, v[122:125] offset:32768
	s_waitcnt vmcnt(1)
	ds_write_b128 v212, v[126:129] offset:32768
	s_waitcnt vmcnt(0)
	ds_write_b128 v213, v[130:133] offset:32768
	ds_write_b128 v214, v[114:117]
	ds_write_b128 v215, v[118:121]
	s_waitcnt lgkmcnt(0)
	s_barrier
	s_cbranch_scc1 .LBB0_885
	v_lshl_add_u64 v[192:193], s[0:1], 0, v[0:1]
	v_add_u32_e32 v0, s10, v209
	v_mov_b32_e32 v14, v1
	v_mov_b32_e32 v15, v1
	s_add_i32 s82, s10, s5
	v_subrev_u32_e32 v221, s4, v0
	v_mov_b32_e32 v0, v1
	v_mov_b32_e32 v2, v1
	v_mov_b32_e32 v3, v1
	v_mov_b32_e32 v4, v1
	v_mov_b32_e32 v5, v1
	v_mov_b32_e32 v6, v1
	v_mov_b32_e32 v7, v1
	v_mov_b32_e32 v8, v1
	v_mov_b32_e32 v9, v1
	v_mov_b32_e32 v10, v1
	v_mov_b32_e32 v11, v1
	v_mov_b32_e32 v12, v1
	v_mov_b32_e32 v13, v1
	v_mov_b64_e32 v[64:65], v[14:15]
	v_mov_b64_e32 v[48:49], v[14:15]
	v_mov_b64_e32 v[32:33], v[14:15]
	v_writelane_b32 v255, s28, 46
	s_add_u32 s78, s92, s11
	v_mov_b64_e32 v[62:63], v[12:13]
	v_mov_b64_e32 v[60:61], v[10:11]
	v_mov_b64_e32 v[58:59], v[8:9]
	v_mov_b64_e32 v[56:57], v[6:7]
	v_mov_b64_e32 v[54:55], v[4:5]
	v_mov_b64_e32 v[52:53], v[2:3]
	v_mov_b64_e32 v[50:51], v[0:1]
	v_mov_b64_e32 v[46:47], v[12:13]
	v_mov_b64_e32 v[44:45], v[10:11]
	v_mov_b64_e32 v[42:43], v[8:9]
	v_mov_b64_e32 v[40:41], v[6:7]
	v_mov_b64_e32 v[38:39], v[4:5]
	v_mov_b64_e32 v[36:37], v[2:3]
	v_mov_b64_e32 v[34:35], v[0:1]
	v_mov_b64_e32 v[30:31], v[12:13]
	v_mov_b64_e32 v[28:29], v[10:11]
	v_mov_b64_e32 v[26:27], v[8:9]
	v_mov_b64_e32 v[24:25], v[6:7]
	v_mov_b64_e32 v[22:23], v[4:5]
	v_mov_b64_e32 v[20:21], v[2:3]
	v_mov_b64_e32 v[18:19], v[0:1]
	v_mov_b64_e32 v[16:17], v[14:15]
	v_writelane_b32 v255, s29, 47
	s_mov_b32 s83, 2
	s_addc_u32 s79, s93, 0
	s_mov_b32 s84, 0
	v_mov_b32_e32 v224, 0xf149f2ca
	v_mov_b32_e32 v219, 0
	v_mov_b64_e32 v[14:15], v[12:13]
	v_mov_b64_e32 v[12:13], v[10:11]
	v_mov_b64_e32 v[10:11], v[8:9]
	v_mov_b64_e32 v[8:9], v[6:7]
	v_mov_b64_e32 v[6:7], v[4:5]
	v_mov_b64_e32 v[4:5], v[2:3]
	v_mov_b64_e32 v[2:3], v[0:1]
	s_branch .LBB0_732
